# v13 + attention: -inf constant held in temp v251 and used as v_cndmask src0 (59 v_mov removed from the VALU-bound softmax mask code)
# baseline (speedup 1.0000x reference)
; #define LAS __attribute__((address_space(3)))
; __device__ __forceinline__ void attn_unit(LAS unsigned char* lds, bf16_t* proj, const float* biasG, const float* sink, int s, int qb, int kh, int hp, bf16_t* dummy = nullptr) {
;     ...
;         for (int si = 0; si < 4; ++si) {
;             const int st = kbi * 4 + si;
;             if (st < wq || st > wq + 8) continue;
;             f32x4 sa[2][2];
; #pragma unroll
;             for (int kt = 0; kt < 2; ++kt) { sa[kt][0] = (f32x4){0.f, 0.f, 0.f, 0.f}; sa[kt][1] = (f32x4){0.f, 0.f, 0.f, 0.f}; }
; #pragma unroll
;             for (int ks = 0; ks < 4; ++ks)
; #pragma unroll
;                 for (int kt = 0; kt < 2; ++kt) {
;                     const bf16x8 kf = *(const LAS bf16x8*)(Ks + (si * 32 + kt * 16 + l16) * 272 + ks * 64 + kg * 16);
;                     sa[kt][0] = __builtin_amdgcn_mfma_f32_16x16x32_bf16(kf, qf[0][ks], sa[kt][0], 0, 0, 0);
;                     sa[kt][1] = __builtin_amdgcn_mfma_f32_16x16x32_bf16(kf, qf[1][ks], sa[kt][1], 0, 0, 0);
;                 }
;             bf16x8 pf[2];
; #pragma unroll
;             for (int qt = 0; qt < 2; ++qt) {
;                 const int qp = wq * 32 + qt * 16 + l16;
;                 float sv[8]; float mx = -1e30f;
; #pragma unroll
;                 for (int kt = 0; kt < 2; ++kt)
; #pragma unroll
;                     for (int r = 0; r < 4; ++r) {
;                         const int kp = (kbi - 1) * 128 + si * 32 + kt * 16 + kg * 4 + r;
;                         const int rel = kp - qp; const bool valid = (rel >= -128) && (rel <= 128);
;                         const int idx = min(max(rel + 128, 0), 256);
;                         const float v = valid ? (sa[kt][qt][r] * SC + bL[hl * 260 + idx]) : -1e30f;
;                         sv[kt * 4 + r] = v; mx = fmaxf(mx, v);
;                     }
;                 mx = fmaxf(mx, __shfl_xor(mx, 16)); mx = fmaxf(mx, __shfl_xor(mx, 32));
.LBB0_665:
	s_add_i32 s19, s30, -3
	v_cmp_ge_u32_e32 vcc, s19, v192
	v_cmp_le_u32_e64 s[4:5], s19, v195
	s_and_b64 s[4:5], vcc, s[4:5]
	s_and_saveexec_b64 s[74:75], s[4:5]
	s_cbranch_execz .LBB0_699
	v_add_u32_e32 v251, 0x11700, v200
	v_add_u32_e32 v251, v251, v196
	v_add_u32_e32 v252, 0x11700, v201
	v_add_u32_e32 v252, v252, v196
	ds_read_b32 v235, v252 offset:256
	ds_read_b32 v236, v252 offset:260
	ds_read_b32 v237, v252 offset:264
	ds_read_b32 v238, v252 offset:268
	ds_read_b32 v239, v252 offset:320
	ds_read_b32 v240, v252 offset:324
	ds_read_b32 v241, v252 offset:328
	ds_read_b32 v242, v252 offset:332
	ds_read_b32 v243, v251 offset:192
	ds_read_b32 v244, v251 offset:196
	ds_read_b32 v245, v251 offset:200
	ds_read_b32 v246, v251 offset:204
	ds_read_b32 v247, v252 offset:256
	ds_read_b32 v248, v252 offset:260
	ds_read_b32 v249, v252 offset:264
	ds_read_b32 v250, v252 offset:268
	ds_read_b128 v[132:135], v213
	ds_read_b128 v[226:229], v213 offset:64
	ds_read_b128 v[140:143], v213 offset:4352
	v_add_u32_e32 v1, 0xffffff8d, v199
	v_cmp_gt_u32_e32 vcc, s53, v1
	v_add3_u32 v2, v201, v196, s31
	s_waitcnt lgkmcnt(0)
	v_mfma_f32_16x16x32_bf16 v[136:139], v[132:135], v[4:7], 0
	v_mfma_f32_16x16x32_bf16 v[132:135], v[132:135], v[20:23], 0
	v_mfma_f32_16x16x32_bf16 v[136:139], v[226:229], v[8:11], v[136:139]
	v_mfma_f32_16x16x32_bf16 v[132:135], v[226:229], v[24:27], v[132:135]
	ds_read_b128 v[226:229], v213 offset:4416
	v_mfma_f32_16x16x32_bf16 v[144:147], v[140:143], v[4:7], 0
	v_mfma_f32_16x16x32_bf16 v[140:143], v[140:143], v[20:23], 0
	s_waitcnt lgkmcnt(0)
	v_mfma_f32_16x16x32_bf16 v[144:147], v[226:229], v[8:11], v[144:147]
	v_mfma_f32_16x16x32_bf16 v[140:143], v[226:229], v[24:27], v[140:143]
	ds_read_b128 v[226:229], v213 offset:128
	s_waitcnt lgkmcnt(0)
	v_mfma_f32_16x16x32_bf16 v[136:139], v[226:229], v[12:15], v[136:139]
	v_mfma_f32_16x16x32_bf16 v[132:135], v[226:229], v[28:31], v[132:135]
	ds_read_b128 v[226:229], v213 offset:4480
	s_waitcnt lgkmcnt(0)
	v_mfma_f32_16x16x32_bf16 v[230:233], v[226:229], v[12:15], v[144:147]
	v_mfma_f32_16x16x32_bf16 v[226:229], v[226:229], v[28:31], v[140:143]
	s_nop 2
	ds_read_b128 v[140:143], v213 offset:192
	s_waitcnt lgkmcnt(0)
	v_mfma_f32_16x16x32_bf16 v[144:147], v[140:143], v[16:19], v[136:139]
	s_nop 2
	ds_read_b128 v[136:139], v213 offset:4544
	v_mfma_f32_16x16x32_bf16 v[140:143], v[140:143], v[32:35], v[132:135]
	s_waitcnt lgkmcnt(0)
	v_mfma_f32_16x16x32_bf16 v[132:135], v[136:139], v[16:19], v[230:233]
	v_mfma_f32_16x16x32_bf16 v[136:139], v[136:139], v[32:35], v[226:229]
	s_nop 2
	v_mov_b32_e32 v251, 0xf149f2ca
	s_waitcnt lgkmcnt(0)
	v_fmac_f32_e32 v235, 0x3e0293ee, v144
	v_cndmask_b32_e32 v229, v251, v235, vcc
	v_add_u32_e32 v1, 0xffffff8e, v199
	v_cmp_gt_u32_e64 s[4:5], s53, v1
	v_add3_u32 v225, v201, v196, s40
	v_fmac_f32_e32 v236, 0x3e0293ee, v145
	v_cndmask_b32_e64 v228, v251, v236, s[4:5]
	v_add_u32_e32 v1, 0xffffff8f, v199
	v_cmp_gt_u32_e64 s[6:7], s53, v1
	v_add3_u32 v226, v201, v196, s42
	v_fmac_f32_e32 v237, 0x3e0293ee, v146
	v_cndmask_b32_e64 v230, v251, v237, s[6:7]
	v_add_u32_e32 v1, 0xffffff90, v199
	v_cmp_gt_u32_e64 s[8:9], s53, v1
	v_add3_u32 v227, v201, v196, s96
	v_fmac_f32_e32 v238, 0x3e0293ee, v147
	v_cndmask_b32_e64 v145, v251, v238, s[8:9]
	v_add_u32_e32 v1, 0xffffff9d, v199
	v_cmp_gt_u32_e64 s[10:11], s53, v1
	v_fmac_f32_e32 v239, 0x3e0293ee, v132
	s_nop 0
	v_cndmask_b32_e64 v231, v251, v239, s[10:11]
	v_add_u32_e32 v1, 0xffffff9e, v199
	v_cmp_gt_u32_e64 s[10:11], s53, v1
	v_fmac_f32_e32 v240, 0x3e0293ee, v133
	s_nop 0
	v_cndmask_b32_e64 v232, v251, v240, s[10:11]
	v_add_u32_e32 v1, 0xffffff9f, v199
	v_cmp_gt_u32_e64 s[10:11], s53, v1
	v_fmac_f32_e32 v241, 0x3e0293ee, v134
	s_nop 0
	v_cndmask_b32_e64 v133, v251, v241, s[10:11]
	v_add_u32_e32 v1, 0xffffffa0, v199
	v_cmp_gt_u32_e64 s[10:11], s53, v1
	v_fmac_f32_e32 v242, 0x3e0293ee, v135
	s_nop 0
	v_cndmask_b32_e64 v132, v251, v242, s[10:11]
	v_mov_b32_e32 v144, 0xf149f2ca
	v_and_b32_e32 v134, 64, v182
	v_max3_f32 v1, v229, v144, v228
	v_xor_b32_e32 v3, 16, v182
	v_add_u32_e32 v134, 64, v134
	v_max3_f32 v1, v1, v230, v145
	v_cmp_lt_i32_e64 s[10:11], v3, v134
	v_max3_f32 v1, v1, v231, v232
	v_max3_f32 v1, v1, v133, v132
	v_cndmask_b32_e64 v3, v182, v3, s[10:11]
	v_lshlrev_b32_e32 v146, 2, v3
	v_mov_b32_e32 v253, v1
	v_mov_b32_e32 v135, v1
	s_nop 1
	v_permlane16_swap_b32_e32 v253, v135
	v_max_f32_e32 v135, v135, v253
	v_xor_b32_e32 v3, 32, v182
	v_cmp_lt_i32_e64 s[10:11], v3, v134
	s_waitcnt lgkmcnt(0)
	v_max_f32_e32 v134, v135, v135
	v_cndmask_b32_e64 v3, v182, v3, s[10:11]
	v_lshlrev_b32_e32 v3, 2, v3
	v_max_f32_e32 v1, v1, v134
	v_mov_b32_e32 v253, v1
	v_mov_b32_e32 v134, v1
	s_nop 1
	v_permlane32_swap_b32_e32 v253, v134
	v_max_f32_e32 v134, v134, v253
	s_waitcnt lgkmcnt(0)
; #define LAS __attribute__((address_space(3)))
; __device__ __forceinline__ unsigned cvt_pk_bf16(float lo, float hi) { unsigned r; asm volatile("v_cvt_pk_bf16_f32 %0, %1, %2" : "=v"(r) : "v"(lo), "v"(hi)); return r; }
; __device__ __forceinline__ void attn_unit(LAS unsigned char* lds, bf16_t* proj, const float* biasG, const float* sink, int s, int qb, int kh, int hp, bf16_t* dummy = nullptr) {
;     ...
;                         const int kp = (kbi - 1) * 128 + si * 32 + kt * 16 + kg * 4 + r;
;                         const int rel = kp - qp; const bool valid = (rel >= -128) && (rel <= 128);
;                         const int idx = min(max(rel + 128, 0), 256);
;                         const float v = valid ? (sa[kt][qt][r] * SC + bL[hl * 260 + idx]) : -1e30f;
;                         sv[kt * 4 + r] = v; mx = fmaxf(mx, v);
;                     }
;                 mx = fmaxf(mx, __shfl_xor(mx, 16)); mx = fmaxf(mx, __shfl_xor(mx, 32));
;                 const float mnew = fmaxf(m2[qt], mx), alpha = __builtin_amdgcn_exp2f(m2[qt] - mnew); m2[qt] = mnew;
;                 float ps = 0.f; float pv[8];
; #pragma unroll
;                 for (int i = 0; i < 8; ++i) { pv[i] = __builtin_amdgcn_exp2f(sv[i] - mnew); ps += pv[i]; }
;                 lsum[qt] = lsum[qt] * alpha + ps;
; #pragma unroll
;                 for (int dt = 0; dt < 8; ++dt) o[dt][qt] = o[dt][qt] * alpha;
;                 u32x4 pw; pw.x = cvt_pk_bf16(pv[0], pv[1]); pw.y = cvt_pk_bf16(pv[2], pv[3]); pw.z = cvt_pk_bf16(pv[4], pv[5]); pw.w = cvt_pk_bf16(pv[6], pv[7]);
;                 pf[qt] = __builtin_bit_cast(bf16x8, pw);
;             }
; #pragma unroll
;             for (int dt = 0; dt < 8; ++dt) {
;                 const LAS unsigned char* vr = Vt + (dt * 16 + l16) * 288 + (si * 32 + kg * 4) * 2;
;                 const u32x2 lo = *(const LAS u32x2*)(vr), hi = *(const LAS u32x2*)(vr + 32);
	v_max3_f32 v1, v224, v1, v134
	v_sub_f32_e32 v134, v229, v1
	v_exp_f32_e32 v147, v134
	v_sub_f32_e32 v134, v228, v1
	v_exp_f32_e32 v228, v134
	v_sub_f32_e32 v134, v230, v1
	v_exp_f32_e32 v229, v134
	v_sub_f32_e32 v134, v145, v1
	v_exp_f32_e32 v230, v134
	v_sub_f32_e32 v134, v231, v1
	v_exp_f32_e32 v231, v134
	v_sub_f32_e32 v134, v232, v1
	v_sub_f32_e32 v133, v133, v1
	v_sub_f32_e32 v132, v132, v1
	v_exp_f32_e32 v232, v134
	v_exp_f32_e32 v233, v133
	v_exp_f32_e32 v234, v132
	v_add_u32_e32 v145, 0xffffff7d, v199
	v_cmp_gt_u32_e64 s[10:11], s53, v145
	v_cvt_pk_bf16_f32 v132, v147, v228
	v_cvt_pk_bf16_f32 v133, v229, v230
	v_cvt_pk_bf16_f32 v134, v231, v232
	v_cvt_pk_bf16_f32 v135, v233, v234
	v_fmac_f32_e32 v243, 0x3e0293ee, v140
	v_cndmask_b32_e64 v145, v251, v243, s[10:11]
	v_add_u32_e32 v140, 0xffffff7e, v199
	v_cmp_gt_u32_e64 s[10:11], s53, v140
	v_fmac_f32_e32 v244, 0x3e0293ee, v141
	s_nop 0
	v_cndmask_b32_e64 v144, v144, v244, s[10:11]
	v_add_u32_e32 v140, 0xffffff7f, v199
	v_cmp_gt_u32_e64 s[10:11], s53, v140
	v_fmac_f32_e32 v245, 0x3e0293ee, v142
	s_nop 0
	v_cndmask_b32_e64 v141, v251, v245, s[10:11]
	v_add_u32_e32 v142, 0xffffff80, v199
	v_cmp_gt_u32_e64 s[10:11], s53, v142
	v_fmac_f32_e32 v246, 0x3e0293ee, v143
	s_nop 0
	v_cndmask_b32_e64 v140, v251, v246, s[10:11]
	v_fmac_f32_e32 v247, 0x3e0293ee, v136
	v_cndmask_b32_e32 v143, v251, v247, vcc
	v_fmac_f32_e32 v248, 0x3e0293ee, v137
	v_cndmask_b32_e64 v142, v251, v248, s[4:5]
	v_fmac_f32_e32 v249, 0x3e0293ee, v138
	v_cndmask_b32_e64 v137, v251, v249, s[6:7]
	v_fmac_f32_e32 v250, 0x3e0293ee, v139
	v_cndmask_b32_e64 v136, v251, v250, s[8:9]
	v_max3_f32 v2, v145, s89, v144
	v_max3_f32 v2, v2, v141, v140
	v_max3_f32 v139, v2, v143, v142
	v_add_f32_e32 v2, 0, v147
	v_add_f32_e32 v2, v228, v2
	v_add_f32_e32 v2, v229, v2
	v_sub_f32_e32 v138, v224, v1
	v_add_f32_e32 v2, v230, v2
	v_add_f32_e32 v2, v231, v2
	v_exp_f32_e32 v138, v138
	v_add_f32_e32 v2, v232, v2
	v_add_f32_e32 v2, v233, v2
	v_add_f32_e32 v2, v234, v2
	v_fmac_f32_e32 v2, v223, v138
	v_pk_mul_f32 v[98:99], v[98:99], v[138:139] op_sel_hi:[1,0]
	v_pk_mul_f32 v[96:97], v[96:97], v[138:139] op_sel_hi:[1,0]
	v_pk_mul_f32 v[106:107], v[106:107], v[138:139] op_sel_hi:[1,0]
	v_pk_mul_f32 v[104:105], v[104:105], v[138:139] op_sel_hi:[1,0]
	v_pk_mul_f32 v[110:111], v[110:111], v[138:139] op_sel_hi:[1,0]
	v_pk_mul_f32 v[108:109], v[108:109], v[138:139] op_sel_hi:[1,0]
	v_pk_mul_f32 v[114:115], v[114:115], v[138:139] op_sel_hi:[1,0]
	v_pk_mul_f32 v[112:113], v[112:113], v[138:139] op_sel_hi:[1,0]
	v_pk_mul_f32 v[118:119], v[118:119], v[138:139] op_sel_hi:[1,0]
	v_pk_mul_f32 v[116:117], v[116:117], v[138:139] op_sel_hi:[1,0]
	v_pk_mul_f32 v[122:123], v[122:123], v[138:139] op_sel_hi:[1,0]
	v_pk_mul_f32 v[120:121], v[120:121], v[138:139] op_sel_hi:[1,0]
	v_pk_mul_f32 v[126:127], v[126:127], v[138:139] op_sel_hi:[1,0]
	v_pk_mul_f32 v[124:125], v[124:125], v[138:139] op_sel_hi:[1,0]
	v_pk_mul_f32 v[130:131], v[130:131], v[138:139] op_sel_hi:[1,0]
	v_pk_mul_f32 v[128:129], v[128:129], v[138:139] op_sel_hi:[1,0]
	v_max3_f32 v138, v139, v137, v136
	v_mov_b32_e32 v253, v138
	v_mov_b32_e32 v139, v138
	s_nop 1
	v_permlane16_swap_b32_e32 v253, v139
	v_max_f32_e32 v139, v139, v253
	v_mov_b32_e32 v223, v2
	v_mov_b32_e32 v224, v1
	s_waitcnt lgkmcnt(0)
	v_max_f32_e32 v139, v139, v139
	v_max_f32_e32 v138, v138, v139
	v_mov_b32_e32 v253, v138
	v_mov_b32_e32 v3, v138
	s_nop 1
	v_permlane32_swap_b32_e32 v253, v3
	v_max_f32_e32 v3, v3, v253
	s_waitcnt lgkmcnt(0)
	v_max3_f32 v3, v222, v138, v3
	v_sub_f32_e32 v139, v145, v3
	v_exp_f32_e32 v139, v139
	v_sub_f32_e32 v144, v144, v3
	v_exp_f32_e32 v144, v144
	v_sub_f32_e32 v141, v141, v3
	v_exp_f32_e32 v141, v141
	v_sub_f32_e32 v140, v140, v3
	v_exp_f32_e32 v146, v140
	v_add_f32_e32 v145, 0, v139
	v_sub_f32_e32 v143, v143, v3
	v_add_f32_e32 v145, v144, v145
	v_exp_f32_e32 v143, v143
	v_sub_f32_e32 v142, v142, v3
	v_add_f32_e32 v145, v141, v145
	v_exp_f32_e32 v142, v142
	v_sub_f32_e32 v137, v137, v3
	v_add_f32_e32 v140, v146, v145
	v_exp_f32_e32 v145, v137
	v_sub_f32_e32 v136, v136, v3
	v_sub_f32_e32 v138, v222, v3
	v_exp_f32_e32 v147, v136
	v_add_f32_e32 v140, v143, v140
	v_exp_f32_e32 v136, v138
	v_add_f32_e32 v140, v142, v140
	v_add_f32_e32 v137, v145, v140
	v_add_f32_e32 v140, v147, v137
	v_fmac_f32_e32 v140, v221, v136
	v_pk_mul_f32 v[70:71], v[70:71], v[136:137] op_sel_hi:[1,0]
	v_pk_mul_f32 v[68:69], v[68:69], v[136:137] op_sel_hi:[1,0]
	v_pk_mul_f32 v[74:75], v[74:75], v[136:137] op_sel_hi:[1,0]
	v_pk_mul_f32 v[72:73], v[72:73], v[136:137] op_sel_hi:[1,0]
	v_pk_mul_f32 v[78:79], v[78:79], v[136:137] op_sel_hi:[1,0]
	v_pk_mul_f32 v[76:77], v[76:77], v[136:137] op_sel_hi:[1,0]
	v_pk_mul_f32 v[82:83], v[82:83], v[136:137] op_sel_hi:[1,0]
	v_pk_mul_f32 v[80:81], v[80:81], v[136:137] op_sel_hi:[1,0]
	v_pk_mul_f32 v[86:87], v[86:87], v[136:137] op_sel_hi:[1,0]
	v_pk_mul_f32 v[84:85], v[84:85], v[136:137] op_sel_hi:[1,0]
	v_pk_mul_f32 v[90:91], v[90:91], v[136:137] op_sel_hi:[1,0]
	v_pk_mul_f32 v[88:89], v[88:89], v[136:137] op_sel_hi:[1,0]
	v_pk_mul_f32 v[94:95], v[94:95], v[136:137] op_sel_hi:[1,0]
	v_pk_mul_f32 v[92:93], v[92:93], v[136:137] op_sel_hi:[1,0]
	v_pk_mul_f32 v[102:103], v[102:103], v[136:137] op_sel_hi:[1,0]
	v_pk_mul_f32 v[100:101], v[100:101], v[136:137] op_sel_hi:[1,0]
	v_cvt_pk_bf16_f32 v136, v139, v144
	v_cvt_pk_bf16_f32 v137, v141, v146
	v_add_u32_e32 v141, v197, v198
	v_cvt_pk_bf16_f32 v138, v143, v142
	v_add_u32_e32 v142, 0x8800, v141
	v_cvt_pk_bf16_f32 v139, v145, v147
	ds_read2_b64 v[236:239], v142 offset1:4
	v_mov_b32_e32 v221, v140
	v_add_u32_e32 v252, 0x9800, v141
	ds_read2_b64 v[240:243], v252 offset0:64 offset1:68
	v_add_u32_e32 v252, 0xa800, v141
	ds_read2_b64 v[244:247], v252 offset0:128 offset1:132
	v_add_u32_e32 v252, 0xb800, v141
	ds_read2_b64 v[248:251], v252 offset0:192 offset1:196
	s_waitcnt lgkmcnt(3)
; __device__ __forceinline__ void attn_unit(LAS unsigned char* lds, bf16_t* proj, const float* biasG, const float* sink, int s, int qb, int kh, int hp, bf16_t* dummy = nullptr) {
;     ...
;             if (st < wq || st > wq + 8) continue;
;             f32x4 sa[2][2];
; #pragma unroll
;             for (int kt = 0; kt < 2; ++kt) { sa[kt][0] = (f32x4){0.f, 0.f, 0.f, 0.f}; sa[kt][1] = (f32x4){0.f, 0.f, 0.f, 0.f}; }
; #pragma unroll
;             for (int ks = 0; ks < 4; ++ks)
; #pragma unroll
;                 for (int kt = 0; kt < 2; ++kt) {
;                     const bf16x8 kf = *(const LAS bf16x8*)(Ks + (si * 32 + kt * 16 + l16) * 272 + ks * 64 + kg * 16);
;                     sa[kt][0] = __builtin_amdgcn_mfma_f32_16x16x32_bf16(kf, qf[0][ks], sa[kt][0], 0, 0, 0);
;                     sa[kt][1] = __builtin_amdgcn_mfma_f32_16x16x32_bf16(kf, qf[1][ks], sa[kt][1], 0, 0, 0);
;                 }
;             bf16x8 pf[2];
; #pragma unroll
;             for (int qt = 0; qt < 2; ++qt) {
;                 const int qp = wq * 32 + qt * 16 + l16;
;                 float sv[8]; float mx = -1e30f;
; #pragma unroll
;                 for (int kt = 0; kt < 2; ++kt)
; #pragma unroll
;                     for (int r = 0; r < 4; ++r) {
;                         const int kp = (kbi - 1) * 128 + si * 32 + kt * 16 + kg * 4 + r;
;                         const int rel = kp - qp; const bool valid = (rel >= -128) && (rel <= 128);
;                         const int idx = min(max(rel + 128, 0), 256);
;                         const float v = valid ? (sa[kt][qt][r] * SC + bL[hl * 260 + idx]) : -1e30f;
;                         sv[kt * 4 + r] = v; mx = fmaxf(mx, v);
;                     }
;                 mx = fmaxf(mx, __shfl_xor(mx, 16)); mx = fmaxf(mx, __shfl_xor(mx, 32));
;     ...
;             for (int dt = 0; dt < 8; ++dt) {
;                 const LAS unsigned char* vr = Vt + (dt * 16 + l16) * 288 + (si * 32 + kg * 4) * 2;
;                 const u32x2 lo = *(const LAS u32x2*)(vr), hi = *(const LAS u32x2*)(vr + 32);
;                 u32x4 vw; vw.x = lo.x; vw.y = lo.y; vw.z = hi.x; vw.w = hi.y;
;                 const bf16x8 vf = __builtin_bit_cast(bf16x8, vw);
;                 o[dt][0] = __builtin_amdgcn_mfma_f32_16x16x32_bf16(vf, pf[0], o[dt][0], 0, 0, 0);
;                 o[dt][1] = __builtin_amdgcn_mfma_f32_16x16x32_bf16(vf, pf[1], o[dt][1], 0, 0, 0);
;             }
	v_mfma_f32_16x16x32_bf16 v[96:99], v[236:239], v[132:135], v[96:99]
	v_mov_b32_e32 v222, v3
	v_mfma_f32_16x16x32_bf16 v[68:71], v[236:239], v[136:139], v[68:71]
	v_add_u32_e32 v252, 0xd000, v141
	ds_read2_b64 v[236:239], v252 offset1:4
	s_waitcnt lgkmcnt(3)
	v_mfma_f32_16x16x32_bf16 v[104:107], v[240:243], v[132:135], v[104:107]
	v_mfma_f32_16x16x32_bf16 v[72:75], v[240:243], v[136:139], v[72:75]
	v_add_u32_e32 v252, 0xe000, v141
	ds_read2_b64 v[240:243], v252 offset0:64 offset1:68
	v_add_u32_e32 v141, 0xf000, v141
	s_waitcnt lgkmcnt(3)
	v_mfma_f32_16x16x32_bf16 v[108:111], v[244:247], v[132:135], v[108:111]
	v_mfma_f32_16x16x32_bf16 v[76:79], v[244:247], v[136:139], v[76:79]
	ds_read2_b64 v[244:247], v141 offset0:128 offset1:132
	s_waitcnt lgkmcnt(3)
	v_mfma_f32_16x16x32_bf16 v[112:115], v[248:251], v[132:135], v[112:115]
	v_mfma_f32_16x16x32_bf16 v[80:83], v[248:251], v[136:139], v[80:83]
	ds_read2_b64 v[248:251], v214 offset0:192 offset1:196
	s_waitcnt lgkmcnt(3)
	v_mfma_f32_16x16x32_bf16 v[116:119], v[236:239], v[132:135], v[116:119]
	v_mfma_f32_16x16x32_bf16 v[84:87], v[236:239], v[136:139], v[84:87]
	s_waitcnt lgkmcnt(2)
	v_mfma_f32_16x16x32_bf16 v[120:123], v[240:243], v[132:135], v[120:123]
	v_mfma_f32_16x16x32_bf16 v[88:91], v[240:243], v[136:139], v[88:91]
	s_waitcnt lgkmcnt(1)
	v_mfma_f32_16x16x32_bf16 v[124:127], v[244:247], v[132:135], v[124:127]
	v_mfma_f32_16x16x32_bf16 v[92:95], v[244:247], v[136:139], v[92:95]
	s_waitcnt lgkmcnt(0)
	v_mfma_f32_16x16x32_bf16 v[128:131], v[248:251], v[132:135], v[128:131]
	v_mfma_f32_16x16x32_bf16 v[100:103], v[248:251], v[136:139], v[100:103]
.LBB0_699:
	s_or_b64 exec, exec, s[74:75]
	s_add_i32 s4, s30, -2
	v_cmp_ge_u32_e32 vcc, s4, v192
	v_cmp_lt_u32_e64 s[4:5], s19, v195
	s_and_b64 s[4:5], vcc, s[4:5]
	s_and_saveexec_b64 s[74:75], s[4:5]
	s_cbranch_execz .LBB0_733
	v_add_u32_e32 v251, 0x11700, v201
	v_add_u32_e32 v251, v251, v196
	ds_read_b32 v235, v251 offset:384
	ds_read_b32 v236, v251 offset:388
	ds_read_b32 v237, v251 offset:392
	ds_read_b32 v238, v251 offset:396
	ds_read_b32 v239, v251 offset:448
	ds_read_b32 v240, v251 offset:452
	ds_read_b32 v241, v251 offset:456
	ds_read_b32 v242, v251 offset:460
	ds_read_b32 v243, v251 offset:320
	ds_read_b32 v244, v251 offset:324
	ds_read_b32 v245, v251 offset:328
	ds_read_b32 v246, v251 offset:332
	ds_read_b32 v247, v251 offset:384
	ds_read_b32 v248, v251 offset:388
	ds_read_b32 v249, v251 offset:392
	ds_read_b32 v250, v251 offset:396
	ds_read_b128 v[132:135], v210
	ds_read_b128 v[226:229], v210 offset:64
	ds_read_b128 v[140:143], v213 offset:13056
	v_add_u32_e32 v1, 0xffffffad, v199
	v_cmp_gt_u32_e32 vcc, s53, v1
	v_add3_u32 v2, v201, v196, s88
	s_waitcnt lgkmcnt(0)
	v_mfma_f32_16x16x32_bf16 v[136:139], v[132:135], v[4:7], 0
	v_mfma_f32_16x16x32_bf16 v[132:135], v[132:135], v[20:23], 0
	v_mfma_f32_16x16x32_bf16 v[136:139], v[226:229], v[8:11], v[136:139]
	v_mfma_f32_16x16x32_bf16 v[132:135], v[226:229], v[24:27], v[132:135]
	ds_read_b128 v[226:229], v213 offset:13120
	v_mfma_f32_16x16x32_bf16 v[144:147], v[140:143], v[4:7], 0
	v_mfma_f32_16x16x32_bf16 v[140:143], v[140:143], v[20:23], 0
	s_waitcnt lgkmcnt(0)
	v_mfma_f32_16x16x32_bf16 v[144:147], v[226:229], v[8:11], v[144:147]
	v_mfma_f32_16x16x32_bf16 v[140:143], v[226:229], v[24:27], v[140:143]
	ds_read_b128 v[226:229], v210 offset:128
	s_waitcnt lgkmcnt(0)
	v_mfma_f32_16x16x32_bf16 v[136:139], v[226:229], v[12:15], v[136:139]
	v_mfma_f32_16x16x32_bf16 v[132:135], v[226:229], v[28:31], v[132:135]
	ds_read_b128 v[226:229], v213 offset:13184
	s_waitcnt lgkmcnt(0)
	v_mfma_f32_16x16x32_bf16 v[230:233], v[226:229], v[12:15], v[144:147]
	v_mfma_f32_16x16x32_bf16 v[226:229], v[226:229], v[28:31], v[140:143]
	s_nop 2
	ds_read_b128 v[140:143], v210 offset:192
	s_waitcnt lgkmcnt(0)
	v_mfma_f32_16x16x32_bf16 v[144:147], v[140:143], v[16:19], v[136:139]
	s_nop 2
	ds_read_b128 v[136:139], v213 offset:13248
	v_mfma_f32_16x16x32_bf16 v[140:143], v[140:143], v[32:35], v[132:135]
	s_waitcnt lgkmcnt(0)
	v_mfma_f32_16x16x32_bf16 v[132:135], v[136:139], v[16:19], v[230:233]
	v_mfma_f32_16x16x32_bf16 v[136:139], v[136:139], v[32:35], v[226:229]
	s_nop 2
	v_mov_b32_e32 v251, 0xf149f2ca
	s_waitcnt lgkmcnt(0)
	v_fmac_f32_e32 v235, 0x3e0293ee, v144
	v_cndmask_b32_e32 v229, v251, v235, vcc
	v_add_u32_e32 v1, 0xffffffae, v199
	v_cmp_gt_u32_e64 s[4:5], s53, v1
	v_add3_u32 v225, v201, v196, s55
	v_fmac_f32_e32 v236, 0x3e0293ee, v145
	v_cndmask_b32_e64 v228, v251, v236, s[4:5]
	v_add_u32_e32 v1, 0xffffffaf, v199
	v_cmp_gt_u32_e64 s[6:7], s53, v1
	v_add3_u32 v226, v201, v196, s59
	v_fmac_f32_e32 v237, 0x3e0293ee, v146
	v_cndmask_b32_e64 v230, v251, v237, s[6:7]
	v_add_u32_e32 v1, 0xffffffb0, v199
	v_cmp_gt_u32_e64 s[8:9], s53, v1
	v_add3_u32 v227, v201, v196, s43
	v_fmac_f32_e32 v238, 0x3e0293ee, v147
	v_cndmask_b32_e64 v145, v251, v238, s[8:9]
	v_add_u32_e32 v1, 0xffffffbd, v199
	v_cmp_gt_u32_e64 s[10:11], s53, v1
	v_fmac_f32_e32 v239, 0x3e0293ee, v132
	s_nop 0
	v_cndmask_b32_e64 v231, v251, v239, s[10:11]
	v_add_u32_e32 v1, 0xffffffbe, v199
	v_cmp_gt_u32_e64 s[10:11], s53, v1
	v_fmac_f32_e32 v240, 0x3e0293ee, v133
	s_nop 0
	v_cndmask_b32_e64 v232, v251, v240, s[10:11]
	v_add_u32_e32 v1, 0xffffffbf, v199
	v_cmp_gt_u32_e64 s[10:11], s53, v1
	v_fmac_f32_e32 v241, 0x3e0293ee, v134
	s_nop 0
	v_cndmask_b32_e64 v133, v251, v241, s[10:11]
	v_subrev_u32_e32 v1, 64, v199
	v_cmp_gt_u32_e64 s[10:11], s53, v1
	v_fmac_f32_e32 v242, 0x3e0293ee, v135
	s_nop 0
	v_cndmask_b32_e64 v132, v251, v242, s[10:11]
	v_mov_b32_e32 v144, 0xf149f2ca
	v_and_b32_e32 v134, 64, v182
	v_max3_f32 v1, v229, v144, v228
	v_xor_b32_e32 v3, 16, v182
	v_add_u32_e32 v134, 64, v134
	v_max3_f32 v1, v1, v230, v145
	v_cmp_lt_i32_e64 s[10:11], v3, v134
	v_max3_f32 v1, v1, v231, v232
	v_max3_f32 v1, v1, v133, v132
	v_cndmask_b32_e64 v3, v182, v3, s[10:11]
	v_lshlrev_b32_e32 v146, 2, v3
	v_mov_b32_e32 v253, v1
	v_mov_b32_e32 v135, v1
	s_nop 1
	v_permlane16_swap_b32_e32 v253, v135
	v_max_f32_e32 v135, v135, v253
	v_xor_b32_e32 v3, 32, v182
	v_cmp_lt_i32_e64 s[10:11], v3, v134
	s_waitcnt lgkmcnt(0)
; #define LAS __attribute__((address_space(3)))
; __device__ __forceinline__ unsigned cvt_pk_bf16(float lo, float hi) { unsigned r; asm volatile("v_cvt_pk_bf16_f32 %0, %1, %2" : "=v"(r) : "v"(lo), "v"(hi)); return r; }
; __device__ __forceinline__ void attn_unit(LAS unsigned char* lds, bf16_t* proj, const float* biasG, const float* sink, int s, int qb, int kh, int hp, bf16_t* dummy = nullptr) {
;     ...
;                 float sv[8]; float mx = -1e30f;
; #pragma unroll
;                 for (int kt = 0; kt < 2; ++kt)
; #pragma unroll
;                     for (int r = 0; r < 4; ++r) {
;                         const int kp = (kbi - 1) * 128 + si * 32 + kt * 16 + kg * 4 + r;
;                         const int rel = kp - qp; const bool valid = (rel >= -128) && (rel <= 128);
;                         const int idx = min(max(rel + 128, 0), 256);
;                         const float v = valid ? (sa[kt][qt][r] * SC + bL[hl * 260 + idx]) : -1e30f;
;                         sv[kt * 4 + r] = v; mx = fmaxf(mx, v);
;                     }
;                 mx = fmaxf(mx, __shfl_xor(mx, 16)); mx = fmaxf(mx, __shfl_xor(mx, 32));
;                 const float mnew = fmaxf(m2[qt], mx), alpha = __builtin_amdgcn_exp2f(m2[qt] - mnew); m2[qt] = mnew;
;                 float ps = 0.f; float pv[8];
; #pragma unroll
;                 for (int i = 0; i < 8; ++i) { pv[i] = __builtin_amdgcn_exp2f(sv[i] - mnew); ps += pv[i]; }
;                 lsum[qt] = lsum[qt] * alpha + ps;
; #pragma unroll
;                 for (int dt = 0; dt < 8; ++dt) o[dt][qt] = o[dt][qt] * alpha;
;                 u32x4 pw; pw.x = cvt_pk_bf16(pv[0], pv[1]); pw.y = cvt_pk_bf16(pv[2], pv[3]); pw.z = cvt_pk_bf16(pv[4], pv[5]); pw.w = cvt_pk_bf16(pv[6], pv[7]);
;                 pf[qt] = __builtin_bit_cast(bf16x8, pw);
;             }
; #pragma unroll
;             for (int dt = 0; dt < 8; ++dt) {
;                 const LAS unsigned char* vr = Vt + (dt * 16 + l16) * 288 + (si * 32 + kg * 4) * 2;
;                 const u32x2 lo = *(const LAS u32x2*)(vr), hi = *(const LAS u32x2*)(vr + 32);
	v_max_f32_e32 v134, v135, v135
	v_cndmask_b32_e64 v3, v182, v3, s[10:11]
	v_lshlrev_b32_e32 v3, 2, v3
	v_max_f32_e32 v1, v1, v134
	v_mov_b32_e32 v253, v1
	v_mov_b32_e32 v134, v1
	s_nop 1
	v_permlane32_swap_b32_e32 v253, v134
	v_max_f32_e32 v134, v134, v253
	s_waitcnt lgkmcnt(0)
	v_max3_f32 v1, v224, v1, v134
	v_sub_f32_e32 v134, v229, v1
	v_exp_f32_e32 v147, v134
	v_sub_f32_e32 v134, v228, v1
	v_exp_f32_e32 v228, v134
	v_sub_f32_e32 v134, v230, v1
	v_exp_f32_e32 v229, v134
	v_sub_f32_e32 v134, v145, v1
	v_exp_f32_e32 v230, v134
	v_sub_f32_e32 v134, v231, v1
	v_exp_f32_e32 v231, v134
	v_sub_f32_e32 v134, v232, v1
	v_sub_f32_e32 v133, v133, v1
	v_sub_f32_e32 v132, v132, v1
	v_exp_f32_e32 v232, v134
	v_exp_f32_e32 v233, v133
	v_exp_f32_e32 v234, v132
	v_add_u32_e32 v145, 0xffffff9d, v199
	v_cmp_gt_u32_e64 s[10:11], s53, v145
	v_cvt_pk_bf16_f32 v132, v147, v228
	v_cvt_pk_bf16_f32 v133, v229, v230
	v_cvt_pk_bf16_f32 v134, v231, v232
	v_cvt_pk_bf16_f32 v135, v233, v234
	v_fmac_f32_e32 v243, 0x3e0293ee, v140
	v_cndmask_b32_e64 v145, v251, v243, s[10:11]
	v_add_u32_e32 v140, 0xffffff9e, v199
	v_cmp_gt_u32_e64 s[10:11], s53, v140
	v_fmac_f32_e32 v244, 0x3e0293ee, v141
	s_nop 0
	v_cndmask_b32_e64 v144, v144, v244, s[10:11]
	v_add_u32_e32 v140, 0xffffff9f, v199
	v_cmp_gt_u32_e64 s[10:11], s53, v140
	v_fmac_f32_e32 v245, 0x3e0293ee, v142
	s_nop 0
	v_cndmask_b32_e64 v141, v251, v245, s[10:11]
	v_add_u32_e32 v142, 0xffffffa0, v199
	v_cmp_gt_u32_e64 s[10:11], s53, v142
	v_fmac_f32_e32 v246, 0x3e0293ee, v143
	s_nop 0
	v_cndmask_b32_e64 v140, v251, v246, s[10:11]
	v_fmac_f32_e32 v247, 0x3e0293ee, v136
	v_cndmask_b32_e32 v143, v251, v247, vcc
	v_fmac_f32_e32 v248, 0x3e0293ee, v137
	v_cndmask_b32_e64 v142, v251, v248, s[4:5]
	v_fmac_f32_e32 v249, 0x3e0293ee, v138
	v_cndmask_b32_e64 v137, v251, v249, s[6:7]
	v_fmac_f32_e32 v250, 0x3e0293ee, v139
	v_cndmask_b32_e64 v136, v251, v250, s[8:9]
	v_max3_f32 v2, v145, s89, v144
	v_max3_f32 v2, v2, v141, v140
	v_max3_f32 v139, v2, v143, v142
	v_add_f32_e32 v2, 0, v147
	v_add_f32_e32 v2, v228, v2
	v_add_f32_e32 v2, v229, v2
	v_sub_f32_e32 v138, v224, v1
	v_add_f32_e32 v2, v230, v2
	v_add_f32_e32 v2, v231, v2
	v_exp_f32_e32 v138, v138
	v_add_f32_e32 v2, v232, v2
	v_add_f32_e32 v2, v233, v2
	v_add_f32_e32 v2, v234, v2
	v_fmac_f32_e32 v2, v223, v138
	v_pk_mul_f32 v[98:99], v[98:99], v[138:139] op_sel_hi:[1,0]
	v_pk_mul_f32 v[96:97], v[96:97], v[138:139] op_sel_hi:[1,0]
	v_pk_mul_f32 v[106:107], v[106:107], v[138:139] op_sel_hi:[1,0]
	v_pk_mul_f32 v[104:105], v[104:105], v[138:139] op_sel_hi:[1,0]
	v_pk_mul_f32 v[110:111], v[110:111], v[138:139] op_sel_hi:[1,0]
	v_pk_mul_f32 v[108:109], v[108:109], v[138:139] op_sel_hi:[1,0]
	v_pk_mul_f32 v[114:115], v[114:115], v[138:139] op_sel_hi:[1,0]
	v_pk_mul_f32 v[112:113], v[112:113], v[138:139] op_sel_hi:[1,0]
	v_pk_mul_f32 v[118:119], v[118:119], v[138:139] op_sel_hi:[1,0]
	v_pk_mul_f32 v[116:117], v[116:117], v[138:139] op_sel_hi:[1,0]
	v_pk_mul_f32 v[122:123], v[122:123], v[138:139] op_sel_hi:[1,0]
	v_pk_mul_f32 v[120:121], v[120:121], v[138:139] op_sel_hi:[1,0]
	v_pk_mul_f32 v[126:127], v[126:127], v[138:139] op_sel_hi:[1,0]
	v_pk_mul_f32 v[124:125], v[124:125], v[138:139] op_sel_hi:[1,0]
	v_pk_mul_f32 v[130:131], v[130:131], v[138:139] op_sel_hi:[1,0]
	v_pk_mul_f32 v[128:129], v[128:129], v[138:139] op_sel_hi:[1,0]
	v_max3_f32 v138, v139, v137, v136
	v_mov_b32_e32 v253, v138
	v_mov_b32_e32 v139, v138
	s_nop 1
	v_permlane16_swap_b32_e32 v253, v139
	v_max_f32_e32 v139, v139, v253
	v_mov_b32_e32 v223, v2
	v_mov_b32_e32 v224, v1
	s_waitcnt lgkmcnt(0)
	v_max_f32_e32 v139, v139, v139
	v_max_f32_e32 v138, v138, v139
	v_mov_b32_e32 v253, v138
	v_mov_b32_e32 v3, v138
	s_nop 1
	v_permlane32_swap_b32_e32 v253, v3
	v_max_f32_e32 v3, v3, v253
	s_waitcnt lgkmcnt(0)
	v_max3_f32 v3, v222, v138, v3
	v_sub_f32_e32 v139, v145, v3
	v_exp_f32_e32 v139, v139
	v_sub_f32_e32 v144, v144, v3
	v_exp_f32_e32 v144, v144
	v_sub_f32_e32 v141, v141, v3
	v_exp_f32_e32 v141, v141
	v_sub_f32_e32 v140, v140, v3
	v_exp_f32_e32 v146, v140
	v_add_f32_e32 v145, 0, v139
	v_sub_f32_e32 v143, v143, v3
	v_add_f32_e32 v145, v144, v145
	v_exp_f32_e32 v143, v143
	v_sub_f32_e32 v142, v142, v3
	v_add_f32_e32 v145, v141, v145
	v_exp_f32_e32 v142, v142
	v_sub_f32_e32 v137, v137, v3
	v_add_f32_e32 v140, v146, v145
	v_exp_f32_e32 v145, v137
	v_sub_f32_e32 v136, v136, v3
	v_sub_f32_e32 v138, v222, v3
	v_exp_f32_e32 v147, v136
	v_add_f32_e32 v140, v143, v140
	v_exp_f32_e32 v136, v138
	v_add_f32_e32 v140, v142, v140
	v_add_f32_e32 v137, v145, v140
	v_add_f32_e32 v140, v147, v137
	v_fmac_f32_e32 v140, v221, v136
	v_pk_mul_f32 v[70:71], v[70:71], v[136:137] op_sel_hi:[1,0]
	v_pk_mul_f32 v[68:69], v[68:69], v[136:137] op_sel_hi:[1,0]
	v_pk_mul_f32 v[74:75], v[74:75], v[136:137] op_sel_hi:[1,0]
	v_pk_mul_f32 v[72:73], v[72:73], v[136:137] op_sel_hi:[1,0]
	v_pk_mul_f32 v[78:79], v[78:79], v[136:137] op_sel_hi:[1,0]
	v_pk_mul_f32 v[76:77], v[76:77], v[136:137] op_sel_hi:[1,0]
	v_pk_mul_f32 v[82:83], v[82:83], v[136:137] op_sel_hi:[1,0]
	v_pk_mul_f32 v[80:81], v[80:81], v[136:137] op_sel_hi:[1,0]
	v_pk_mul_f32 v[86:87], v[86:87], v[136:137] op_sel_hi:[1,0]
	v_pk_mul_f32 v[84:85], v[84:85], v[136:137] op_sel_hi:[1,0]
	v_pk_mul_f32 v[90:91], v[90:91], v[136:137] op_sel_hi:[1,0]
	v_pk_mul_f32 v[88:89], v[88:89], v[136:137] op_sel_hi:[1,0]
	v_pk_mul_f32 v[94:95], v[94:95], v[136:137] op_sel_hi:[1,0]
	v_pk_mul_f32 v[92:93], v[92:93], v[136:137] op_sel_hi:[1,0]
	v_pk_mul_f32 v[102:103], v[102:103], v[136:137] op_sel_hi:[1,0]
	v_pk_mul_f32 v[100:101], v[100:101], v[136:137] op_sel_hi:[1,0]
	v_cvt_pk_bf16_f32 v136, v139, v144
	v_cvt_pk_bf16_f32 v137, v141, v146
	v_add_u32_e32 v141, v197, v198
	v_cvt_pk_bf16_f32 v138, v143, v142
	v_add_u32_e32 v142, 0x8800, v141
	v_cvt_pk_bf16_f32 v139, v145, v147
	ds_read2_b64 v[236:239], v142 offset0:8 offset1:12
	v_mov_b32_e32 v221, v140
	v_add_u32_e32 v252, 0x9800, v141
	ds_read2_b64 v[240:243], v252 offset0:72 offset1:76
	ds_read2_b64 v[244:247], v215 offset0:8 offset1:12
	v_add_u32_e32 v252, 0xb800, v141
	ds_read2_b64 v[248:251], v252 offset0:200 offset1:204
	s_waitcnt lgkmcnt(3)
; __device__ __forceinline__ void attn_unit(LAS unsigned char* lds, bf16_t* proj, const float* biasG, const float* sink, int s, int qb, int kh, int hp, bf16_t* dummy = nullptr) {
;     ...
;             if (st < wq || st > wq + 8) continue;
;             f32x4 sa[2][2];
; #pragma unroll
;             for (int kt = 0; kt < 2; ++kt) { sa[kt][0] = (f32x4){0.f, 0.f, 0.f, 0.f}; sa[kt][1] = (f32x4){0.f, 0.f, 0.f, 0.f}; }
; #pragma unroll
;             for (int ks = 0; ks < 4; ++ks)
; #pragma unroll
;                 for (int kt = 0; kt < 2; ++kt) {
;                     const bf16x8 kf = *(const LAS bf16x8*)(Ks + (si * 32 + kt * 16 + l16) * 272 + ks * 64 + kg * 16);
;                     sa[kt][0] = __builtin_amdgcn_mfma_f32_16x16x32_bf16(kf, qf[0][ks], sa[kt][0], 0, 0, 0);
;                     sa[kt][1] = __builtin_amdgcn_mfma_f32_16x16x32_bf16(kf, qf[1][ks], sa[kt][1], 0, 0, 0);
;                 }
;             bf16x8 pf[2];
; #pragma unroll
;             for (int qt = 0; qt < 2; ++qt) {
;                 const int qp = wq * 32 + qt * 16 + l16;
;                 float sv[8]; float mx = -1e30f;
; #pragma unroll
;                 for (int kt = 0; kt < 2; ++kt)
; #pragma unroll
;                     for (int r = 0; r < 4; ++r) {
;                         const int kp = (kbi - 1) * 128 + si * 32 + kt * 16 + kg * 4 + r;
;                         const int rel = kp - qp; const bool valid = (rel >= -128) && (rel <= 128);
;                         const int idx = min(max(rel + 128, 0), 256);
;                         const float v = valid ? (sa[kt][qt][r] * SC + bL[hl * 260 + idx]) : -1e30f;
;                         sv[kt * 4 + r] = v; mx = fmaxf(mx, v);
;                     }
;                 mx = fmaxf(mx, __shfl_xor(mx, 16)); mx = fmaxf(mx, __shfl_xor(mx, 32));
;     ...
;             for (int dt = 0; dt < 8; ++dt) {
;                 const LAS unsigned char* vr = Vt + (dt * 16 + l16) * 288 + (si * 32 + kg * 4) * 2;
;                 const u32x2 lo = *(const LAS u32x2*)(vr), hi = *(const LAS u32x2*)(vr + 32);
;                 u32x4 vw; vw.x = lo.x; vw.y = lo.y; vw.z = hi.x; vw.w = hi.y;
;                 const bf16x8 vf = __builtin_bit_cast(bf16x8, vw);
;                 o[dt][0] = __builtin_amdgcn_mfma_f32_16x16x32_bf16(vf, pf[0], o[dt][0], 0, 0, 0);
;                 o[dt][1] = __builtin_amdgcn_mfma_f32_16x16x32_bf16(vf, pf[1], o[dt][1], 0, 0, 0);
;             }
	v_mfma_f32_16x16x32_bf16 v[96:99], v[236:239], v[132:135], v[96:99]
	v_mov_b32_e32 v222, v3
	v_mfma_f32_16x16x32_bf16 v[68:71], v[236:239], v[136:139], v[68:71]
	v_add_u32_e32 v252, 0xd000, v141
	ds_read2_b64 v[236:239], v252 offset0:8 offset1:12
	s_waitcnt lgkmcnt(3)
	v_mfma_f32_16x16x32_bf16 v[104:107], v[240:243], v[132:135], v[104:107]
	v_mfma_f32_16x16x32_bf16 v[72:75], v[240:243], v[136:139], v[72:75]
	v_add_u32_e32 v252, 0xe000, v141
	ds_read2_b64 v[240:243], v252 offset0:72 offset1:76
	v_add_u32_e32 v141, 0xf000, v141
	s_waitcnt lgkmcnt(3)
	v_mfma_f32_16x16x32_bf16 v[108:111], v[244:247], v[132:135], v[108:111]
	v_mfma_f32_16x16x32_bf16 v[76:79], v[244:247], v[136:139], v[76:79]
	ds_read2_b64 v[244:247], v141 offset0:136 offset1:140
	s_waitcnt lgkmcnt(3)
	v_mfma_f32_16x16x32_bf16 v[112:115], v[248:251], v[132:135], v[112:115]
	v_mfma_f32_16x16x32_bf16 v[80:83], v[248:251], v[136:139], v[80:83]
	ds_read2_b64 v[248:251], v216 offset0:192 offset1:196
	s_waitcnt lgkmcnt(3)
	v_mfma_f32_16x16x32_bf16 v[116:119], v[236:239], v[132:135], v[116:119]
	v_mfma_f32_16x16x32_bf16 v[84:87], v[236:239], v[136:139], v[84:87]
	s_waitcnt lgkmcnt(2)
	v_mfma_f32_16x16x32_bf16 v[120:123], v[240:243], v[132:135], v[120:123]
	v_mfma_f32_16x16x32_bf16 v[88:91], v[240:243], v[136:139], v[88:91]
	s_waitcnt lgkmcnt(1)
	v_mfma_f32_16x16x32_bf16 v[124:127], v[244:247], v[132:135], v[124:127]
	v_mfma_f32_16x16x32_bf16 v[92:95], v[244:247], v[136:139], v[92:95]
	s_waitcnt lgkmcnt(0)
	v_mfma_f32_16x16x32_bf16 v[128:131], v[248:251], v[132:135], v[128:131]
	v_mfma_f32_16x16x32_bf16 v[100:103], v[248:251], v[136:139], v[100:103]
.LBB0_733:
	s_or_b64 exec, exec, s[74:75]
	s_add_i32 s4, s30, -1
	v_cmp_ge_u32_e32 vcc, s4, v192
	v_cmp_le_u32_e64 s[4:5], s4, v195
	s_and_b64 s[4:5], vcc, s[4:5]
	s_and_saveexec_b64 s[74:75], s[4:5]
	s_cbranch_execz .LBB0_767
	v_add_u32_e32 v251, 0x11700, v201
	v_add_u32_e32 v251, v251, v196
	ds_read_b32 v235, v251 offset:512
	ds_read_b32 v236, v251 offset:516
	ds_read_b32 v237, v251 offset:520
	ds_read_b32 v238, v251 offset:524
	ds_read_b32 v239, v251 offset:576
	ds_read_b32 v240, v251 offset:580
	ds_read_b32 v241, v251 offset:584
	ds_read_b32 v242, v251 offset:588
	ds_read_b32 v243, v251 offset:448
	ds_read_b32 v244, v251 offset:452
	ds_read_b32 v245, v251 offset:456
	ds_read_b32 v246, v251 offset:460
	ds_read_b32 v247, v251 offset:512
	ds_read_b32 v248, v251 offset:516
	ds_read_b32 v249, v251 offset:520
	ds_read_b32 v250, v251 offset:524
	ds_read_b128 v[132:135], v211
	ds_read_b128 v[226:229], v211 offset:64
	ds_read_b128 v[140:143], v213 offset:21760
	v_subrev_u32_e32 v1, 51, v199
	v_cmp_gt_u32_e32 vcc, s53, v1
	v_add3_u32 v2, v201, v196, s14
	s_waitcnt lgkmcnt(0)
	v_mfma_f32_16x16x32_bf16 v[136:139], v[132:135], v[4:7], 0
	v_mfma_f32_16x16x32_bf16 v[132:135], v[132:135], v[20:23], 0
	v_mfma_f32_16x16x32_bf16 v[136:139], v[226:229], v[8:11], v[136:139]
	v_mfma_f32_16x16x32_bf16 v[132:135], v[226:229], v[24:27], v[132:135]
	ds_read_b128 v[226:229], v213 offset:21824
	v_mfma_f32_16x16x32_bf16 v[144:147], v[140:143], v[4:7], 0
	v_mfma_f32_16x16x32_bf16 v[140:143], v[140:143], v[20:23], 0
	s_waitcnt lgkmcnt(0)
	v_mfma_f32_16x16x32_bf16 v[144:147], v[226:229], v[8:11], v[144:147]
	v_mfma_f32_16x16x32_bf16 v[140:143], v[226:229], v[24:27], v[140:143]
	ds_read_b128 v[226:229], v211 offset:128
	s_waitcnt lgkmcnt(0)
	v_mfma_f32_16x16x32_bf16 v[136:139], v[226:229], v[12:15], v[136:139]
	v_mfma_f32_16x16x32_bf16 v[132:135], v[226:229], v[28:31], v[132:135]
	ds_read_b128 v[226:229], v213 offset:21888
	s_waitcnt lgkmcnt(0)
	v_mfma_f32_16x16x32_bf16 v[230:233], v[226:229], v[12:15], v[144:147]
	v_mfma_f32_16x16x32_bf16 v[226:229], v[226:229], v[28:31], v[140:143]
	s_nop 2
	ds_read_b128 v[140:143], v211 offset:192
	s_waitcnt lgkmcnt(0)
	v_mfma_f32_16x16x32_bf16 v[144:147], v[140:143], v[16:19], v[136:139]
	s_nop 2
	ds_read_b128 v[136:139], v213 offset:21952
	v_mfma_f32_16x16x32_bf16 v[140:143], v[140:143], v[32:35], v[132:135]
	s_waitcnt lgkmcnt(0)
	v_mfma_f32_16x16x32_bf16 v[132:135], v[136:139], v[16:19], v[230:233]
	v_mfma_f32_16x16x32_bf16 v[136:139], v[136:139], v[32:35], v[226:229]
	s_nop 2
	v_mov_b32_e32 v251, 0xf149f2ca
	s_waitcnt lgkmcnt(0)
	v_fmac_f32_e32 v235, 0x3e0293ee, v144
	v_cndmask_b32_e32 v229, v251, v235, vcc
	v_subrev_u32_e32 v1, 50, v199
	v_cmp_gt_u32_e64 s[4:5], s53, v1
	v_add3_u32 v225, v201, v196, s54
	v_fmac_f32_e32 v236, 0x3e0293ee, v145
	v_cndmask_b32_e64 v228, v251, v236, s[4:5]
	v_subrev_u32_e32 v1, 49, v199
	v_cmp_gt_u32_e64 s[6:7], s53, v1
	v_add3_u32 v226, v201, v196, s58
	v_fmac_f32_e32 v237, 0x3e0293ee, v146
	v_cndmask_b32_e64 v230, v251, v237, s[6:7]
	v_subrev_u32_e32 v1, 48, v199
	v_cmp_gt_u32_e64 s[8:9], s53, v1
	v_add3_u32 v227, v201, v196, s97
	v_fmac_f32_e32 v238, 0x3e0293ee, v147
	v_cndmask_b32_e64 v145, v251, v238, s[8:9]
	v_subrev_u32_e32 v1, 35, v199
	v_cmp_gt_u32_e64 s[10:11], s53, v1
	v_fmac_f32_e32 v239, 0x3e0293ee, v132
	s_nop 0
	v_cndmask_b32_e64 v231, v251, v239, s[10:11]
	v_subrev_u32_e32 v1, 34, v199
	v_cmp_gt_u32_e64 s[10:11], s53, v1
	v_fmac_f32_e32 v240, 0x3e0293ee, v133
	s_nop 0
	v_cndmask_b32_e64 v232, v251, v240, s[10:11]
	v_subrev_u32_e32 v1, 33, v199
	v_cmp_gt_u32_e64 s[10:11], s53, v1
	v_fmac_f32_e32 v241, 0x3e0293ee, v134
	s_nop 0
	v_cndmask_b32_e64 v133, v251, v241, s[10:11]
	v_subrev_u32_e32 v1, 32, v199
	v_cmp_gt_u32_e64 s[10:11], s53, v1
	v_fmac_f32_e32 v242, 0x3e0293ee, v135
	s_nop 0
	v_cndmask_b32_e64 v132, v251, v242, s[10:11]
	v_mov_b32_e32 v144, 0xf149f2ca
	v_and_b32_e32 v134, 64, v182
	v_max3_f32 v1, v229, v144, v228
	v_xor_b32_e32 v3, 16, v182
	v_add_u32_e32 v134, 64, v134
	v_max3_f32 v1, v1, v230, v145
	v_cmp_lt_i32_e64 s[10:11], v3, v134
	v_max3_f32 v1, v1, v231, v232
	v_max3_f32 v1, v1, v133, v132
	v_cndmask_b32_e64 v3, v182, v3, s[10:11]
	v_lshlrev_b32_e32 v146, 2, v3
	v_mov_b32_e32 v253, v1
	v_mov_b32_e32 v135, v1
	s_nop 1
	v_permlane16_swap_b32_e32 v253, v135
	v_max_f32_e32 v135, v135, v253
	v_xor_b32_e32 v3, 32, v182
	v_cmp_lt_i32_e64 s[10:11], v3, v134
	s_waitcnt lgkmcnt(0)
; #define LAS __attribute__((address_space(3)))
; __device__ __forceinline__ unsigned cvt_pk_bf16(float lo, float hi) { unsigned r; asm volatile("v_cvt_pk_bf16_f32 %0, %1, %2" : "=v"(r) : "v"(lo), "v"(hi)); return r; }
; __device__ __forceinline__ void attn_unit(LAS unsigned char* lds, bf16_t* proj, const float* biasG, const float* sink, int s, int qb, int kh, int hp, bf16_t* dummy = nullptr) {
;     ...
;                 float sv[8]; float mx = -1e30f;
; #pragma unroll
;                 for (int kt = 0; kt < 2; ++kt)
; #pragma unroll
;                     for (int r = 0; r < 4; ++r) {
;                         const int kp = (kbi - 1) * 128 + si * 32 + kt * 16 + kg * 4 + r;
;                         const int rel = kp - qp; const bool valid = (rel >= -128) && (rel <= 128);
;                         const int idx = min(max(rel + 128, 0), 256);
;                         const float v = valid ? (sa[kt][qt][r] * SC + bL[hl * 260 + idx]) : -1e30f;
;                         sv[kt * 4 + r] = v; mx = fmaxf(mx, v);
;                     }
;                 mx = fmaxf(mx, __shfl_xor(mx, 16)); mx = fmaxf(mx, __shfl_xor(mx, 32));
;                 const float mnew = fmaxf(m2[qt], mx), alpha = __builtin_amdgcn_exp2f(m2[qt] - mnew); m2[qt] = mnew;
;                 float ps = 0.f; float pv[8];
; #pragma unroll
;                 for (int i = 0; i < 8; ++i) { pv[i] = __builtin_amdgcn_exp2f(sv[i] - mnew); ps += pv[i]; }
;                 lsum[qt] = lsum[qt] * alpha + ps;
; #pragma unroll
;                 for (int dt = 0; dt < 8; ++dt) o[dt][qt] = o[dt][qt] * alpha;
;                 u32x4 pw; pw.x = cvt_pk_bf16(pv[0], pv[1]); pw.y = cvt_pk_bf16(pv[2], pv[3]); pw.z = cvt_pk_bf16(pv[4], pv[5]); pw.w = cvt_pk_bf16(pv[6], pv[7]);
;                 pf[qt] = __builtin_bit_cast(bf16x8, pw);
;             }
; #pragma unroll
;             for (int dt = 0; dt < 8; ++dt) {
;                 const LAS unsigned char* vr = Vt + (dt * 16 + l16) * 288 + (si * 32 + kg * 4) * 2;
;                 const u32x2 lo = *(const LAS u32x2*)(vr), hi = *(const LAS u32x2*)(vr + 32);
	v_max_f32_e32 v134, v135, v135
	v_cndmask_b32_e64 v3, v182, v3, s[10:11]
	v_lshlrev_b32_e32 v3, 2, v3
	v_max_f32_e32 v1, v1, v134
	v_mov_b32_e32 v253, v1
	v_mov_b32_e32 v134, v1
	s_nop 1
	v_permlane32_swap_b32_e32 v253, v134
	v_max_f32_e32 v134, v134, v253
	s_waitcnt lgkmcnt(0)
	v_max3_f32 v1, v224, v1, v134
	v_sub_f32_e32 v134, v229, v1
	v_exp_f32_e32 v147, v134
	v_sub_f32_e32 v134, v228, v1
	v_exp_f32_e32 v228, v134
	v_sub_f32_e32 v134, v230, v1
	v_exp_f32_e32 v229, v134
	v_sub_f32_e32 v134, v145, v1
	v_exp_f32_e32 v230, v134
	v_sub_f32_e32 v134, v231, v1
	v_exp_f32_e32 v231, v134
	v_sub_f32_e32 v134, v232, v1
	v_sub_f32_e32 v133, v133, v1
	v_sub_f32_e32 v132, v132, v1
	v_exp_f32_e32 v232, v134
	v_exp_f32_e32 v233, v133
	v_exp_f32_e32 v234, v132
	v_add_u32_e32 v145, 0xffffffbd, v199
	v_cmp_gt_u32_e64 s[10:11], s53, v145
	v_cvt_pk_bf16_f32 v132, v147, v228
	v_cvt_pk_bf16_f32 v133, v229, v230
	v_cvt_pk_bf16_f32 v134, v231, v232
	v_cvt_pk_bf16_f32 v135, v233, v234
	v_fmac_f32_e32 v243, 0x3e0293ee, v140
	v_cndmask_b32_e64 v145, v251, v243, s[10:11]
	v_add_u32_e32 v140, 0xffffffbe, v199
	v_cmp_gt_u32_e64 s[10:11], s53, v140
	v_fmac_f32_e32 v244, 0x3e0293ee, v141
	s_nop 0
	v_cndmask_b32_e64 v144, v144, v244, s[10:11]
	v_add_u32_e32 v140, 0xffffffbf, v199
	v_cmp_gt_u32_e64 s[10:11], s53, v140
	v_fmac_f32_e32 v245, 0x3e0293ee, v142
	s_nop 0
	v_cndmask_b32_e64 v141, v251, v245, s[10:11]
	v_subrev_u32_e32 v142, 64, v199
	v_cmp_gt_u32_e64 s[10:11], s53, v142
	v_fmac_f32_e32 v246, 0x3e0293ee, v143
	s_nop 0
	v_cndmask_b32_e64 v140, v251, v246, s[10:11]
	v_fmac_f32_e32 v247, 0x3e0293ee, v136
	v_cndmask_b32_e32 v143, v251, v247, vcc
	v_fmac_f32_e32 v248, 0x3e0293ee, v137
	v_cndmask_b32_e64 v142, v251, v248, s[4:5]
	v_fmac_f32_e32 v249, 0x3e0293ee, v138
	v_cndmask_b32_e64 v137, v251, v249, s[6:7]
	v_fmac_f32_e32 v250, 0x3e0293ee, v139
	v_cndmask_b32_e64 v136, v251, v250, s[8:9]
	v_max3_f32 v2, v145, s89, v144
	v_max3_f32 v2, v2, v141, v140
	v_max3_f32 v139, v2, v143, v142
	v_add_f32_e32 v2, 0, v147
	v_add_f32_e32 v2, v228, v2
	v_add_f32_e32 v2, v229, v2
	v_sub_f32_e32 v138, v224, v1
	v_add_f32_e32 v2, v230, v2
	v_add_f32_e32 v2, v231, v2
	v_exp_f32_e32 v138, v138
	v_add_f32_e32 v2, v232, v2
	v_add_f32_e32 v2, v233, v2
	v_add_f32_e32 v2, v234, v2
	v_fmac_f32_e32 v2, v223, v138
	v_pk_mul_f32 v[98:99], v[98:99], v[138:139] op_sel_hi:[1,0]
	v_pk_mul_f32 v[96:97], v[96:97], v[138:139] op_sel_hi:[1,0]
	v_pk_mul_f32 v[106:107], v[106:107], v[138:139] op_sel_hi:[1,0]
	v_pk_mul_f32 v[104:105], v[104:105], v[138:139] op_sel_hi:[1,0]
	v_pk_mul_f32 v[110:111], v[110:111], v[138:139] op_sel_hi:[1,0]
	v_pk_mul_f32 v[108:109], v[108:109], v[138:139] op_sel_hi:[1,0]
	v_pk_mul_f32 v[114:115], v[114:115], v[138:139] op_sel_hi:[1,0]
	v_pk_mul_f32 v[112:113], v[112:113], v[138:139] op_sel_hi:[1,0]
	v_pk_mul_f32 v[118:119], v[118:119], v[138:139] op_sel_hi:[1,0]
	v_pk_mul_f32 v[116:117], v[116:117], v[138:139] op_sel_hi:[1,0]
	v_pk_mul_f32 v[122:123], v[122:123], v[138:139] op_sel_hi:[1,0]
	v_pk_mul_f32 v[120:121], v[120:121], v[138:139] op_sel_hi:[1,0]
	v_pk_mul_f32 v[126:127], v[126:127], v[138:139] op_sel_hi:[1,0]
	v_pk_mul_f32 v[124:125], v[124:125], v[138:139] op_sel_hi:[1,0]
	v_pk_mul_f32 v[130:131], v[130:131], v[138:139] op_sel_hi:[1,0]
	v_pk_mul_f32 v[128:129], v[128:129], v[138:139] op_sel_hi:[1,0]
	v_max3_f32 v138, v139, v137, v136
	v_mov_b32_e32 v253, v138
	v_mov_b32_e32 v139, v138
	s_nop 1
	v_permlane16_swap_b32_e32 v253, v139
	v_max_f32_e32 v139, v139, v253
	v_mov_b32_e32 v223, v2
	v_mov_b32_e32 v224, v1
	s_waitcnt lgkmcnt(0)
	v_max_f32_e32 v139, v139, v139
	v_max_f32_e32 v138, v138, v139
	v_mov_b32_e32 v253, v138
	v_mov_b32_e32 v3, v138
	s_nop 1
	v_permlane32_swap_b32_e32 v253, v3
	v_max_f32_e32 v3, v3, v253
	s_waitcnt lgkmcnt(0)
	v_max3_f32 v3, v222, v138, v3
	v_sub_f32_e32 v139, v145, v3
	v_exp_f32_e32 v139, v139
	v_sub_f32_e32 v144, v144, v3
	v_exp_f32_e32 v144, v144
	v_sub_f32_e32 v141, v141, v3
	v_exp_f32_e32 v141, v141
	v_sub_f32_e32 v140, v140, v3
	v_exp_f32_e32 v146, v140
	v_add_f32_e32 v145, 0, v139
	v_sub_f32_e32 v143, v143, v3
	v_add_f32_e32 v145, v144, v145
	v_exp_f32_e32 v143, v143
	v_sub_f32_e32 v142, v142, v3
	v_add_f32_e32 v145, v141, v145
	v_exp_f32_e32 v142, v142
	v_sub_f32_e32 v137, v137, v3
	v_add_f32_e32 v140, v146, v145
	v_exp_f32_e32 v145, v137
	v_sub_f32_e32 v136, v136, v3
	v_sub_f32_e32 v138, v222, v3
	v_exp_f32_e32 v147, v136
	v_add_f32_e32 v140, v143, v140
	v_exp_f32_e32 v136, v138
	v_add_f32_e32 v140, v142, v140
	v_add_f32_e32 v137, v145, v140
	v_add_f32_e32 v140, v147, v137
	v_fmac_f32_e32 v140, v221, v136
	v_pk_mul_f32 v[70:71], v[70:71], v[136:137] op_sel_hi:[1,0]
	v_pk_mul_f32 v[68:69], v[68:69], v[136:137] op_sel_hi:[1,0]
	v_pk_mul_f32 v[74:75], v[74:75], v[136:137] op_sel_hi:[1,0]
	v_pk_mul_f32 v[72:73], v[72:73], v[136:137] op_sel_hi:[1,0]
	v_pk_mul_f32 v[78:79], v[78:79], v[136:137] op_sel_hi:[1,0]
	v_pk_mul_f32 v[76:77], v[76:77], v[136:137] op_sel_hi:[1,0]
	v_pk_mul_f32 v[82:83], v[82:83], v[136:137] op_sel_hi:[1,0]
	v_pk_mul_f32 v[80:81], v[80:81], v[136:137] op_sel_hi:[1,0]
	v_pk_mul_f32 v[86:87], v[86:87], v[136:137] op_sel_hi:[1,0]
	v_pk_mul_f32 v[84:85], v[84:85], v[136:137] op_sel_hi:[1,0]
	v_pk_mul_f32 v[90:91], v[90:91], v[136:137] op_sel_hi:[1,0]
	v_pk_mul_f32 v[88:89], v[88:89], v[136:137] op_sel_hi:[1,0]
	v_pk_mul_f32 v[94:95], v[94:95], v[136:137] op_sel_hi:[1,0]
	v_pk_mul_f32 v[92:93], v[92:93], v[136:137] op_sel_hi:[1,0]
	v_pk_mul_f32 v[102:103], v[102:103], v[136:137] op_sel_hi:[1,0]
	v_pk_mul_f32 v[100:101], v[100:101], v[136:137] op_sel_hi:[1,0]
	v_cvt_pk_bf16_f32 v136, v139, v144
	v_cvt_pk_bf16_f32 v137, v141, v146
	v_add_u32_e32 v141, v197, v198
	v_cvt_pk_bf16_f32 v138, v143, v142
	v_add_u32_e32 v142, 0x8800, v141
	v_cvt_pk_bf16_f32 v139, v145, v147
	ds_read2_b64 v[236:239], v142 offset0:16 offset1:20
	v_mov_b32_e32 v221, v140
	v_add_u32_e32 v252, 0x9800, v141
	ds_read2_b64 v[240:243], v252 offset0:80 offset1:84
	v_add_u32_e32 v252, 0xa800, v141
	ds_read2_b64 v[244:247], v252 offset0:144 offset1:148
	v_add_u32_e32 v252, 0xb800, v141
	ds_read2_b64 v[248:251], v252 offset0:208 offset1:212
	s_waitcnt lgkmcnt(3)
; #define LAS __attribute__((address_space(3)))
; __device__ __forceinline__ void attn_unit(LAS unsigned char* lds, bf16_t* proj, const float* biasG, const float* sink, int s, int qb, int kh, int hp, bf16_t* dummy = nullptr) {
;     ...
;             for (int dt = 0; dt < 8; ++dt) {
;                 const LAS unsigned char* vr = Vt + (dt * 16 + l16) * 288 + (si * 32 + kg * 4) * 2;
;                 const u32x2 lo = *(const LAS u32x2*)(vr), hi = *(const LAS u32x2*)(vr + 32);
;                 u32x4 vw; vw.x = lo.x; vw.y = lo.y; vw.z = hi.x; vw.w = hi.y;
;                 const bf16x8 vf = __builtin_bit_cast(bf16x8, vw);
;                 o[dt][0] = __builtin_amdgcn_mfma_f32_16x16x32_bf16(vf, pf[0], o[dt][0], 0, 0, 0);
;                 o[dt][1] = __builtin_amdgcn_mfma_f32_16x16x32_bf16(vf, pf[1], o[dt][1], 0, 0, 0);
;             }
	v_mfma_f32_16x16x32_bf16 v[96:99], v[236:239], v[132:135], v[96:99]
	v_mov_b32_e32 v222, v3
	v_mfma_f32_16x16x32_bf16 v[68:71], v[236:239], v[136:139], v[68:71]
	ds_read2_b64 v[236:239], v217 offset0:16 offset1:20
	s_waitcnt lgkmcnt(3)
	v_mfma_f32_16x16x32_bf16 v[104:107], v[240:243], v[132:135], v[104:107]
	v_mfma_f32_16x16x32_bf16 v[72:75], v[240:243], v[136:139], v[72:75]
	v_add_u32_e32 v252, 0xe000, v141
	ds_read2_b64 v[240:243], v252 offset0:80 offset1:84
	v_add_u32_e32 v141, 0xf000, v141
	s_waitcnt lgkmcnt(3)
	v_mfma_f32_16x16x32_bf16 v[108:111], v[244:247], v[132:135], v[108:111]
	v_mfma_f32_16x16x32_bf16 v[76:79], v[244:247], v[136:139], v[76:79]
	ds_read2_b64 v[244:247], v141 offset0:144 offset1:148
	s_waitcnt lgkmcnt(3)
	v_mfma_f32_16x16x32_bf16 v[112:115], v[248:251], v[132:135], v[112:115]
	v_mfma_f32_16x16x32_bf16 v[80:83], v[248:251], v[136:139], v[80:83]
	ds_read2_b64 v[248:251], v218 offset0:192 offset1:196
	s_waitcnt lgkmcnt(3)
	v_mfma_f32_16x16x32_bf16 v[116:119], v[236:239], v[132:135], v[116:119]
	v_mfma_f32_16x16x32_bf16 v[84:87], v[236:239], v[136:139], v[84:87]
	s_waitcnt lgkmcnt(2)
	v_mfma_f32_16x16x32_bf16 v[120:123], v[240:243], v[132:135], v[120:123]
	v_mfma_f32_16x16x32_bf16 v[88:91], v[240:243], v[136:139], v[88:91]
	s_waitcnt lgkmcnt(1)
	v_mfma_f32_16x16x32_bf16 v[124:127], v[244:247], v[132:135], v[124:127]
	v_mfma_f32_16x16x32_bf16 v[92:95], v[244:247], v[136:139], v[92:95]
	s_waitcnt lgkmcnt(0)
	v_mfma_f32_16x16x32_bf16 v[128:131], v[248:251], v[132:135], v[128:131]
	v_mfma_f32_16x16x32_bf16 v[100:103], v[248:251], v[136:139], v[100:103]
; #define LAS __attribute__((address_space(3)))
; __device__ __forceinline__ void attn_unit(LAS unsigned char* lds, bf16_t* proj, const float* biasG, const float* sink, int s, int qb, int kh, int hp, bf16_t* dummy = nullptr) {
;     ...
;         for (int si = 0; si < 4; ++si) {
;             const int st = kbi * 4 + si;
;             if (st < wq || st > wq + 8) continue;
;             f32x4 sa[2][2];
; #pragma unroll
;             for (int kt = 0; kt < 2; ++kt) { sa[kt][0] = (f32x4){0.f, 0.f, 0.f, 0.f}; sa[kt][1] = (f32x4){0.f, 0.f, 0.f, 0.f}; }
; #pragma unroll
;             for (int ks = 0; ks < 4; ++ks)
; #pragma unroll
;                 for (int kt = 0; kt < 2; ++kt) {
;                     const bf16x8 kf = *(const LAS bf16x8*)(Ks + (si * 32 + kt * 16 + l16) * 272 + ks * 64 + kg * 16);
;                     sa[kt][0] = __builtin_amdgcn_mfma_f32_16x16x32_bf16(kf, qf[0][ks], sa[kt][0], 0, 0, 0);
;                     sa[kt][1] = __builtin_amdgcn_mfma_f32_16x16x32_bf16(kf, qf[1][ks], sa[kt][1], 0, 0, 0);
;                 }
;             bf16x8 pf[2];
; #pragma unroll
;             for (int qt = 0; qt < 2; ++qt) {
;                 const int qp = wq * 32 + qt * 16 + l16;
;                 float sv[8]; float mx = -1e30f;
; #pragma unroll
;                 for (int kt = 0; kt < 2; ++kt)
; #pragma unroll
;                     for (int r = 0; r < 4; ++r) {
;                         const int kp = (kbi - 1) * 128 + si * 32 + kt * 16 + kg * 4 + r;
;                         const int rel = kp - qp; const bool valid = (rel >= -128) && (rel <= 128);
;                         const int idx = min(max(rel + 128, 0), 256);
;                         const float v = valid ? (sa[kt][qt][r] * SC + bL[hl * 260 + idx]) : -1e30f;
;                         sv[kt * 4 + r] = v; mx = fmaxf(mx, v);
;                     }
;                 mx = fmaxf(mx, __shfl_xor(mx, 16)); mx = fmaxf(mx, __shfl_xor(mx, 32));
.LBB0_767:
	s_or_b64 exec, exec, s[74:75]
	v_cmp_le_u32_e32 vcc, s30, v195
	s_and_saveexec_b64 s[74:75], vcc
	s_cbranch_execz .LBB0_662
	v_add_u32_e32 v251, 0x11700, v201
	v_add_u32_e32 v251, v251, v196
	ds_read_b32 v235, v251 offset:640
	ds_read_b32 v236, v251 offset:644
	ds_read_b32 v237, v251 offset:648
	ds_read_b32 v238, v251 offset:652
	ds_read_b32 v239, v251 offset:704
	ds_read_b32 v240, v251 offset:708
	ds_read_b32 v241, v251 offset:712
	ds_read_b32 v242, v251 offset:716
	ds_read_b32 v243, v251 offset:576
	ds_read_b32 v244, v251 offset:580
	ds_read_b32 v245, v251 offset:584
	ds_read_b32 v246, v251 offset:588
	ds_read_b32 v247, v251 offset:640
	ds_read_b32 v248, v251 offset:644
	ds_read_b32 v249, v251 offset:648
	ds_read_b32 v250, v251 offset:652
	ds_read_b128 v[132:135], v212
	ds_read_b128 v[226:229], v212 offset:64
	ds_read_b128 v[140:143], v213 offset:30464
	v_subrev_u32_e32 v1, 19, v199
	v_cmp_gt_u32_e32 vcc, s53, v1
	v_add3_u32 v2, v201, v196, s49
	s_waitcnt lgkmcnt(0)
	v_mfma_f32_16x16x32_bf16 v[136:139], v[132:135], v[4:7], 0
	v_mfma_f32_16x16x32_bf16 v[132:135], v[132:135], v[20:23], 0
	v_mfma_f32_16x16x32_bf16 v[136:139], v[226:229], v[8:11], v[136:139]
	v_mfma_f32_16x16x32_bf16 v[132:135], v[226:229], v[24:27], v[132:135]
	ds_read_b128 v[226:229], v213 offset:30528
	v_mfma_f32_16x16x32_bf16 v[144:147], v[140:143], v[4:7], 0
	v_mfma_f32_16x16x32_bf16 v[140:143], v[140:143], v[20:23], 0
	s_waitcnt lgkmcnt(0)
	v_mfma_f32_16x16x32_bf16 v[144:147], v[226:229], v[8:11], v[144:147]
	v_mfma_f32_16x16x32_bf16 v[140:143], v[226:229], v[24:27], v[140:143]
	ds_read_b128 v[226:229], v212 offset:128
	s_waitcnt lgkmcnt(0)
	v_mfma_f32_16x16x32_bf16 v[136:139], v[226:229], v[12:15], v[136:139]
	v_mfma_f32_16x16x32_bf16 v[132:135], v[226:229], v[28:31], v[132:135]
	ds_read_b128 v[226:229], v213 offset:30592
	s_waitcnt lgkmcnt(0)
	v_mfma_f32_16x16x32_bf16 v[230:233], v[226:229], v[12:15], v[144:147]
	v_mfma_f32_16x16x32_bf16 v[226:229], v[226:229], v[28:31], v[140:143]
	s_nop 2
	ds_read_b128 v[140:143], v212 offset:192
	s_waitcnt lgkmcnt(0)
	v_mfma_f32_16x16x32_bf16 v[144:147], v[140:143], v[16:19], v[136:139]
	s_nop 2
	ds_read_b128 v[136:139], v213 offset:30656
	v_mfma_f32_16x16x32_bf16 v[140:143], v[140:143], v[32:35], v[132:135]
	s_waitcnt lgkmcnt(0)
	v_mfma_f32_16x16x32_bf16 v[132:135], v[136:139], v[16:19], v[230:233]
	v_mfma_f32_16x16x32_bf16 v[136:139], v[136:139], v[32:35], v[226:229]
	s_nop 2
	v_mov_b32_e32 v251, 0xf149f2ca
	s_waitcnt lgkmcnt(0)
	v_fmac_f32_e32 v235, 0x3e0293ee, v144
	v_cndmask_b32_e32 v229, v251, v235, vcc
	v_subrev_u32_e32 v1, 18, v199
	v_cmp_gt_u32_e64 s[4:5], s53, v1
	v_add3_u32 v225, v201, v196, s0
	v_fmac_f32_e32 v236, 0x3e0293ee, v145
	v_cndmask_b32_e64 v228, v251, v236, s[4:5]
	v_subrev_u32_e32 v1, 17, v199
	v_cmp_gt_u32_e64 s[6:7], s53, v1
	v_add3_u32 v226, v201, v196, s1
	v_fmac_f32_e32 v237, 0x3e0293ee, v146
	v_cndmask_b32_e64 v230, v251, v237, s[6:7]
	v_add_u32_e32 v1, -16, v199
	v_cmp_gt_u32_e64 s[8:9], s53, v1
	v_add3_u32 v227, v201, v196, s15
	v_fmac_f32_e32 v238, 0x3e0293ee, v147
	v_cndmask_b32_e64 v145, v251, v238, s[8:9]
	v_add_u32_e32 v1, -3, v199
	v_cmp_gt_u32_e64 s[10:11], s53, v1
	v_fmac_f32_e32 v239, 0x3e0293ee, v132
	s_nop 0
	v_cndmask_b32_e64 v231, v251, v239, s[10:11]
	v_add_u32_e32 v1, -2, v199
	v_cmp_gt_u32_e64 s[10:11], s53, v1
	v_fmac_f32_e32 v240, 0x3e0293ee, v133
	s_nop 0
	v_cndmask_b32_e64 v232, v251, v240, s[10:11]
	v_add_u32_e32 v1, -1, v199
	v_cmp_gt_u32_e64 s[10:11], s53, v1
	v_fmac_f32_e32 v241, 0x3e0293ee, v134
	s_nop 0
	v_cndmask_b32_e64 v133, v251, v241, s[10:11]
	v_cmp_gt_u32_e64 s[10:11], s53, v199
	v_fmac_f32_e32 v242, 0x3e0293ee, v135
	s_nop 0
	v_cndmask_b32_e64 v132, v251, v242, s[10:11]
	v_mov_b32_e32 v144, 0xf149f2ca
	v_and_b32_e32 v134, 64, v182
	v_max3_f32 v1, v229, v144, v228
	v_xor_b32_e32 v3, 16, v182
	v_add_u32_e32 v134, 64, v134
	v_max3_f32 v1, v1, v230, v145
	v_cmp_lt_i32_e64 s[10:11], v3, v134
	v_max3_f32 v1, v1, v231, v232
	v_max3_f32 v1, v1, v133, v132
	v_cndmask_b32_e64 v3, v182, v3, s[10:11]
	v_lshlrev_b32_e32 v146, 2, v3
	v_mov_b32_e32 v253, v1
	v_mov_b32_e32 v135, v1
	s_nop 1
	v_permlane16_swap_b32_e32 v253, v135
	v_max_f32_e32 v135, v135, v253
	v_xor_b32_e32 v3, 32, v182
	v_cmp_lt_i32_e64 s[10:11], v3, v134
	s_waitcnt lgkmcnt(0)
	v_max_f32_e32 v134, v135, v135
	v_cndmask_b32_e64 v3, v182, v3, s[10:11]
	v_lshlrev_b32_e32 v3, 2, v3
	v_max_f32_e32 v1, v1, v134
	v_mov_b32_e32 v253, v1
	v_mov_b32_e32 v134, v1
	s_nop 1
	v_permlane32_swap_b32_e32 v253, v134
	v_max_f32_e32 v134, v134, v253
	s_waitcnt lgkmcnt(0)
	v_max3_f32 v1, v224, v1, v134
	v_sub_f32_e32 v134, v229, v1
	v_exp_f32_e32 v147, v134
	v_sub_f32_e32 v134, v228, v1
	v_exp_f32_e32 v228, v134
	v_sub_f32_e32 v134, v230, v1
	v_exp_f32_e32 v229, v134
	v_sub_f32_e32 v134, v145, v1
	v_exp_f32_e32 v230, v134
	v_sub_f32_e32 v134, v231, v1
	v_exp_f32_e32 v231, v134
	v_sub_f32_e32 v134, v232, v1
	v_sub_f32_e32 v133, v133, v1
	v_sub_f32_e32 v132, v132, v1
	v_exp_f32_e32 v232, v134
	v_exp_f32_e32 v233, v133
	v_exp_f32_e32 v234, v132
	v_subrev_u32_e32 v145, 35, v199
	v_cmp_gt_u32_e64 s[10:11], s53, v145
	v_cvt_pk_bf16_f32 v132, v147, v228
	v_cvt_pk_bf16_f32 v133, v229, v230
	v_cvt_pk_bf16_f32 v134, v231, v232
	v_cvt_pk_bf16_f32 v135, v233, v234
	v_fmac_f32_e32 v243, 0x3e0293ee, v140
	v_cndmask_b32_e64 v145, v251, v243, s[10:11]
	v_subrev_u32_e32 v140, 34, v199
	v_cmp_gt_u32_e64 s[10:11], s53, v140
	v_fmac_f32_e32 v244, 0x3e0293ee, v141
	s_nop 0
	v_cndmask_b32_e64 v144, v144, v244, s[10:11]
	v_subrev_u32_e32 v140, 33, v199
	v_cmp_gt_u32_e64 s[10:11], s53, v140
	v_fmac_f32_e32 v245, 0x3e0293ee, v142
	s_nop 0
	v_cndmask_b32_e64 v141, v251, v245, s[10:11]
	v_subrev_u32_e32 v142, 32, v199
	v_cmp_gt_u32_e64 s[10:11], s53, v142
	v_fmac_f32_e32 v246, 0x3e0293ee, v143
	s_nop 0
	v_cndmask_b32_e64 v140, v251, v246, s[10:11]
	v_fmac_f32_e32 v247, 0x3e0293ee, v136
	v_cndmask_b32_e32 v143, v251, v247, vcc
	v_fmac_f32_e32 v248, 0x3e0293ee, v137
	v_cndmask_b32_e64 v142, v251, v248, s[4:5]
	v_mov_b32_e32 v136, 0xf149f2ca
	v_fmac_f32_e32 v249, 0x3e0293ee, v138
	v_cndmask_b32_e64 v137, v251, v249, s[6:7]
	s_and_saveexec_b64 s[4:5], s[8:9]
	s_cbranch_execz .LBB0_661
	v_mov_b32_e32 v136, v250
	v_fmac_f32_e32 v136, 0x3e0293ee, v139
	s_branch .LBB0_661
